# baseline (speedup 1.0000x reference)
.LBB0_9:
	s_and_b32 s30, s19, 0xff
	s_cmp_lg_u32 s30, 0
	s_mov_b64 s[34:35], -1
	s_sleep 3
	s_cbranch_scc1 .LBB0_12
	global_load_dword v3, v2, s[16:17] sc1
	s_waitcnt vmcnt(0)
	v_cmp_eq_u32_e32 vcc, 0, v3
	s_cbranch_vccnz .LBB0_14
	s_mov_b64 s[34:35], 0
	s_mov_b64 s[30:31], -1

; __global__ void __launch_bounds__(NTHREADS) fwd_megakernel(Params p_unused) {
;     ...
;   {
;     CParamsPtr k = fresh_params();
;     if (k->ws == nullptr) grid.sync();
;   }
.LBB0_88:
	s_sleep 3
	global_load_dword v2, v0, s[12:13] offset:32 sc1
	s_waitcnt vmcnt(0)
	v_and_b32_e32 v2, 0xffff0000, v2
	v_cmp_ne_u32_e32 vcc, v2, v1
	s_or_b64 s[14:15], vcc, s[14:15]
	s_andn2_b64 exec, exec, s[14:15]
	s_cbranch_execnz .LBB0_88

; __device__ __forceinline__ unsigned xb_ld(unsigned* p) { return __hip_atomic_load(p, __ATOMIC_RELAXED, __HIP_MEMORY_SCOPE_AGENT); }
; __device__ __forceinline__ unsigned xb_add(unsigned* p, unsigned v) { return __hip_atomic_fetch_add(p, v, __ATOMIC_RELAXED, __HIP_MEMORY_SCOPE_AGENT); }
; #define XB_SPIN(cond, bar) do { unsigned _sp = 0; while (cond) { __builtin_amdgcn_s_sleep(1); \
;     if ((++_sp & 255u) == 0u) { if (xb_ld(&(bar)[XB_TMO])) break; if (_sp > XB_SPIN_CAP) { atomicAdd(&(bar)[XB_TMO], 1u); break; } } } } while (0)
; __device__ __forceinline__ void xcd_barrier(const XcdBarrier& b) {
;     ...
;       const unsigned tg = og / b.nx;
;       if (og + 1u == (tg + 1u) * b.nx) xb_add(&bar[XB_TOPGEN], 1u);
;       else XB_SPIN(xb_ld(&bar[XB_TOPGEN]) == tg, bar);
;       __builtin_amdgcn_fence(__ATOMIC_ACQUIRE, "agent");
;       xb_add(&bar[XB_XGEN(b.x)], 1u);
;     } else {
;       XB_SPIN(xb_ld(&bar[XB_XGEN(b.x)]) == gen, bar);
;       __builtin_amdgcn_fence(__ATOMIC_ACQUIRE, "agent");
.LBB0_98:
	s_and_b32 s34, s38, 0xff
	s_mov_b64 s[30:31], -1
	s_cmp_lg_u32 s34, 0
	s_mov_b64 s[36:37], -1
	s_sleep 3
	s_cbranch_scc1 .LBB0_101
	global_load_dword v2, v1, s[16:17] sc1
	s_waitcnt vmcnt(0)
	v_cmp_eq_u32_e32 vcc, 0, v2
	s_cbranch_vccnz .LBB0_103
	s_mov_b64 s[36:37], 0
	s_mov_b64 s[34:35], -1

; __device__ __forceinline__ unsigned xb_ld(unsigned* p) { return __hip_atomic_load(p, __ATOMIC_RELAXED, __HIP_MEMORY_SCOPE_AGENT); }
; __device__ __forceinline__ unsigned xb_add(unsigned* p, unsigned v) { return __hip_atomic_fetch_add(p, v, __ATOMIC_RELAXED, __HIP_MEMORY_SCOPE_AGENT); }
; #define XB_SPIN(cond, bar) do { unsigned _sp = 0; while (cond) { __builtin_amdgcn_s_sleep(1); \
;     if ((++_sp & 255u) == 0u) { if (xb_ld(&(bar)[XB_TMO])) break; if (_sp > XB_SPIN_CAP) { atomicAdd(&(bar)[XB_TMO], 1u); break; } } } } while (0)
; __device__ __forceinline__ void xcd_barrier(const XcdBarrier& b) {
;     ...
;       const unsigned tg = og / b.nx;
;       if (og + 1u == (tg + 1u) * b.nx) xb_add(&bar[XB_TOPGEN], 1u);
;       else XB_SPIN(xb_ld(&bar[XB_TOPGEN]) == tg, bar);
;       __builtin_amdgcn_fence(__ATOMIC_ACQUIRE, "agent");
;       xb_add(&bar[XB_XGEN(b.x)], 1u);
;     } else {
;       XB_SPIN(xb_ld(&bar[XB_XGEN(b.x)]) == gen, bar);
;       __builtin_amdgcn_fence(__ATOMIC_ACQUIRE, "agent");
.LBB0_115:
	s_and_b32 s30, s38, 0xff
	s_cmp_lg_u32 s30, 0
	s_mov_b64 s[34:35], -1
	s_sleep 3
	s_cbranch_scc1 .LBB0_118
	global_load_dword v1, v0, s[16:17] sc1
	s_waitcnt vmcnt(0)
	v_cmp_eq_u32_e32 vcc, 0, v1
	s_cbranch_vccnz .LBB0_120
	s_mov_b64 s[34:35], 0
	s_mov_b64 s[30:31], -1

; __device__ __forceinline__ unsigned xb_ld(unsigned* p) { return __hip_atomic_load(p, __ATOMIC_RELAXED, __HIP_MEMORY_SCOPE_AGENT); }
; __device__ __forceinline__ unsigned xb_add(unsigned* p, unsigned v) { return __hip_atomic_fetch_add(p, v, __ATOMIC_RELAXED, __HIP_MEMORY_SCOPE_AGENT); }
; #define XB_SPIN(cond, bar) do { unsigned _sp = 0; while (cond) { __builtin_amdgcn_s_sleep(1); \
;     if ((++_sp & 255u) == 0u) { if (xb_ld(&(bar)[XB_TMO])) break; if (_sp > XB_SPIN_CAP) { atomicAdd(&(bar)[XB_TMO], 1u); break; } } } } while (0)
; __device__ __forceinline__ void xcd_barrier(const XcdBarrier& b) {
;     ...
;       const unsigned tg = og / b.nx;
;       if (og + 1u == (tg + 1u) * b.nx) xb_add(&bar[XB_TOPGEN], 1u);
;       else XB_SPIN(xb_ld(&bar[XB_TOPGEN]) == tg, bar);
;       __builtin_amdgcn_fence(__ATOMIC_ACQUIRE, "agent");
;       xb_add(&bar[XB_XGEN(b.x)], 1u);
;     } else {
;       XB_SPIN(xb_ld(&bar[XB_XGEN(b.x)]) == gen, bar);
;       __builtin_amdgcn_fence(__ATOMIC_ACQUIRE, "agent");
.LBB0_166:
	s_and_b32 s34, s38, 0xff
	s_mov_b64 s[30:31], -1
	s_cmp_lg_u32 s34, 0
	s_mov_b64 s[36:37], -1
	s_sleep 3
	s_cbranch_scc1 .LBB0_169
	global_load_dword v2, v1, s[14:15] sc1
	s_waitcnt vmcnt(0)
	v_cmp_eq_u32_e32 vcc, 0, v2
	s_cbranch_vccnz .LBB0_171
	s_mov_b64 s[36:37], 0
	s_mov_b64 s[34:35], -1

; __device__ __forceinline__ unsigned xb_ld(unsigned* p) { return __hip_atomic_load(p, __ATOMIC_RELAXED, __HIP_MEMORY_SCOPE_AGENT); }
; __device__ __forceinline__ unsigned xb_add(unsigned* p, unsigned v) { return __hip_atomic_fetch_add(p, v, __ATOMIC_RELAXED, __HIP_MEMORY_SCOPE_AGENT); }
; #define XB_SPIN(cond, bar) do { unsigned _sp = 0; while (cond) { __builtin_amdgcn_s_sleep(1); \
;     if ((++_sp & 255u) == 0u) { if (xb_ld(&(bar)[XB_TMO])) break; if (_sp > XB_SPIN_CAP) { atomicAdd(&(bar)[XB_TMO], 1u); break; } } } } while (0)
; __device__ __forceinline__ void xcd_barrier(const XcdBarrier& b) {
;     ...
;       const unsigned tg = og / b.nx;
;       if (og + 1u == (tg + 1u) * b.nx) xb_add(&bar[XB_TOPGEN], 1u);
;       else XB_SPIN(xb_ld(&bar[XB_TOPGEN]) == tg, bar);
;       __builtin_amdgcn_fence(__ATOMIC_ACQUIRE, "agent");
;       xb_add(&bar[XB_XGEN(b.x)], 1u);
;     } else {
;       XB_SPIN(xb_ld(&bar[XB_XGEN(b.x)]) == gen, bar);
;       __builtin_amdgcn_fence(__ATOMIC_ACQUIRE, "agent");
.LBB0_183:
	s_and_b32 s30, s38, 0xff
	s_cmp_lg_u32 s30, 0
	s_mov_b64 s[34:35], -1
	s_sleep 3
	s_cbranch_scc1 .LBB0_186
	global_load_dword v1, v0, s[14:15] sc1
	s_waitcnt vmcnt(0)
	v_cmp_eq_u32_e32 vcc, 0, v1
	s_cbranch_vccnz .LBB0_188
	s_mov_b64 s[34:35], 0
	s_mov_b64 s[30:31], -1

; __device__ __forceinline__ unsigned xb_ld(unsigned* p) { return __hip_atomic_load(p, __ATOMIC_RELAXED, __HIP_MEMORY_SCOPE_AGENT); }
; __device__ __forceinline__ unsigned xb_add(unsigned* p, unsigned v) { return __hip_atomic_fetch_add(p, v, __ATOMIC_RELAXED, __HIP_MEMORY_SCOPE_AGENT); }
; #define XB_SPIN(cond, bar) do { unsigned _sp = 0; while (cond) { __builtin_amdgcn_s_sleep(1); \
;     if ((++_sp & 255u) == 0u) { if (xb_ld(&(bar)[XB_TMO])) break; if (_sp > XB_SPIN_CAP) { atomicAdd(&(bar)[XB_TMO], 1u); break; } } } } while (0)
; __device__ __forceinline__ void xcd_barrier(const XcdBarrier& b) {
;     ...
;       const unsigned tg = og / b.nx;
;       if (og + 1u == (tg + 1u) * b.nx) xb_add(&bar[XB_TOPGEN], 1u);
;       else XB_SPIN(xb_ld(&bar[XB_TOPGEN]) == tg, bar);
;       __builtin_amdgcn_fence(__ATOMIC_ACQUIRE, "agent");
;       xb_add(&bar[XB_XGEN(b.x)], 1u);
;     } else {
;       XB_SPIN(xb_ld(&bar[XB_XGEN(b.x)]) == gen, bar);
;       __builtin_amdgcn_fence(__ATOMIC_ACQUIRE, "agent");
.LBB0_224:
	s_and_b32 s36, s25, 0xff
	s_mov_b64 s[34:35], -1
	s_cmp_lg_u32 s36, 0
	s_mov_b64 s[38:39], -1
	s_sleep 3
	s_cbranch_scc1 .LBB0_227
	global_load_dword v2, v1, s[14:15] sc1
	s_waitcnt vmcnt(0)
	v_cmp_eq_u32_e32 vcc, 0, v2
	s_cbranch_vccnz .LBB0_229
	s_mov_b64 s[38:39], 0
	s_mov_b64 s[36:37], -1

; __device__ __forceinline__ unsigned xb_ld(unsigned* p) { return __hip_atomic_load(p, __ATOMIC_RELAXED, __HIP_MEMORY_SCOPE_AGENT); }
; __device__ __forceinline__ unsigned xb_add(unsigned* p, unsigned v) { return __hip_atomic_fetch_add(p, v, __ATOMIC_RELAXED, __HIP_MEMORY_SCOPE_AGENT); }
; #define XB_SPIN(cond, bar) do { unsigned _sp = 0; while (cond) { __builtin_amdgcn_s_sleep(1); \
;     if ((++_sp & 255u) == 0u) { if (xb_ld(&(bar)[XB_TMO])) break; if (_sp > XB_SPIN_CAP) { atomicAdd(&(bar)[XB_TMO], 1u); break; } } } } while (0)
; __device__ __forceinline__ void xcd_barrier(const XcdBarrier& b) {
;     ...
;       const unsigned tg = og / b.nx;
;       if (og + 1u == (tg + 1u) * b.nx) xb_add(&bar[XB_TOPGEN], 1u);
;       else XB_SPIN(xb_ld(&bar[XB_TOPGEN]) == tg, bar);
;       __builtin_amdgcn_fence(__ATOMIC_ACQUIRE, "agent");
;       xb_add(&bar[XB_XGEN(b.x)], 1u);
;     } else {
;       XB_SPIN(xb_ld(&bar[XB_XGEN(b.x)]) == gen, bar);
;       __builtin_amdgcn_fence(__ATOMIC_ACQUIRE, "agent");
.LBB0_241:
	s_and_b32 s34, s25, 0xff
	s_cmp_lg_u32 s34, 0
	s_mov_b64 s[36:37], -1
	s_sleep 3
	s_cbranch_scc1 .LBB0_244
	global_load_dword v1, v0, s[14:15] sc1
	s_waitcnt vmcnt(0)
	v_cmp_eq_u32_e32 vcc, 0, v1
	s_cbranch_vccnz .LBB0_246
	s_mov_b64 s[36:37], 0
	s_mov_b64 s[34:35], -1

; __device__ __forceinline__ unsigned xb_ld(unsigned* p) { return __hip_atomic_load(p, __ATOMIC_RELAXED, __HIP_MEMORY_SCOPE_AGENT); }
; __device__ __forceinline__ unsigned xb_add(unsigned* p, unsigned v) { return __hip_atomic_fetch_add(p, v, __ATOMIC_RELAXED, __HIP_MEMORY_SCOPE_AGENT); }
; #define XB_SPIN(cond, bar) do { unsigned _sp = 0; while (cond) { __builtin_amdgcn_s_sleep(1); \
;     if ((++_sp & 255u) == 0u) { if (xb_ld(&(bar)[XB_TMO])) break; if (_sp > XB_SPIN_CAP) { atomicAdd(&(bar)[XB_TMO], 1u); break; } } } } while (0)
; __device__ __forceinline__ void xcd_barrier(const XcdBarrier& b) {
;     ...
;       const unsigned tg = og / b.nx;
;       if (og + 1u == (tg + 1u) * b.nx) xb_add(&bar[XB_TOPGEN], 1u);
;       else XB_SPIN(xb_ld(&bar[XB_TOPGEN]) == tg, bar);
;       __builtin_amdgcn_fence(__ATOMIC_ACQUIRE, "agent");
;       xb_add(&bar[XB_XGEN(b.x)], 1u);
;     } else {
;       XB_SPIN(xb_ld(&bar[XB_XGEN(b.x)]) == gen, bar);
;       __builtin_amdgcn_fence(__ATOMIC_ACQUIRE, "agent");
.LBB0_354:
	s_and_b32 s38, s25, 0xff
	s_mov_b64 s[36:37], -1
	s_cmp_lg_u32 s38, 0
	s_mov_b64 s[40:41], -1
	s_sleep 3
	s_cbranch_scc1 .LBB0_357
	global_load_dword v2, v1, s[14:15] sc1
	s_waitcnt vmcnt(0)
	v_cmp_eq_u32_e32 vcc, 0, v2
	s_cbranch_vccnz .LBB0_359
	s_mov_b64 s[40:41], 0
	s_mov_b64 s[38:39], -1

; __device__ __forceinline__ unsigned xb_ld(unsigned* p) { return __hip_atomic_load(p, __ATOMIC_RELAXED, __HIP_MEMORY_SCOPE_AGENT); }
; __device__ __forceinline__ unsigned xb_add(unsigned* p, unsigned v) { return __hip_atomic_fetch_add(p, v, __ATOMIC_RELAXED, __HIP_MEMORY_SCOPE_AGENT); }
; #define XB_SPIN(cond, bar) do { unsigned _sp = 0; while (cond) { __builtin_amdgcn_s_sleep(1); \
;     if ((++_sp & 255u) == 0u) { if (xb_ld(&(bar)[XB_TMO])) break; if (_sp > XB_SPIN_CAP) { atomicAdd(&(bar)[XB_TMO], 1u); break; } } } } while (0)
; __device__ __forceinline__ void xcd_barrier(const XcdBarrier& b) {
;     ...
;       const unsigned tg = og / b.nx;
;       if (og + 1u == (tg + 1u) * b.nx) xb_add(&bar[XB_TOPGEN], 1u);
;       else XB_SPIN(xb_ld(&bar[XB_TOPGEN]) == tg, bar);
;       __builtin_amdgcn_fence(__ATOMIC_ACQUIRE, "agent");
;       xb_add(&bar[XB_XGEN(b.x)], 1u);
;     } else {
;       XB_SPIN(xb_ld(&bar[XB_XGEN(b.x)]) == gen, bar);
;       __builtin_amdgcn_fence(__ATOMIC_ACQUIRE, "agent");
.LBB0_371:
	s_and_b32 s36, s25, 0xff
	s_cmp_lg_u32 s36, 0
	s_mov_b64 s[38:39], -1
	s_sleep 3
	s_cbranch_scc1 .LBB0_374
	global_load_dword v1, v0, s[14:15] sc1
	s_waitcnt vmcnt(0)
	v_cmp_eq_u32_e32 vcc, 0, v1
	s_cbranch_vccnz .LBB0_376
	s_mov_b64 s[38:39], 0
	s_mov_b64 s[36:37], -1

; __device__ __forceinline__ unsigned xb_ld(unsigned* p) { return __hip_atomic_load(p, __ATOMIC_RELAXED, __HIP_MEMORY_SCOPE_AGENT); }
; __device__ __forceinline__ unsigned xb_add(unsigned* p, unsigned v) { return __hip_atomic_fetch_add(p, v, __ATOMIC_RELAXED, __HIP_MEMORY_SCOPE_AGENT); }
; #define XB_SPIN(cond, bar) do { unsigned _sp = 0; while (cond) { __builtin_amdgcn_s_sleep(1); \
;     if ((++_sp & 255u) == 0u) { if (xb_ld(&(bar)[XB_TMO])) break; if (_sp > XB_SPIN_CAP) { atomicAdd(&(bar)[XB_TMO], 1u); break; } } } } while (0)
; __device__ __forceinline__ void xcd_barrier(const XcdBarrier& b) {
;     ...
;       const unsigned tg = og / b.nx;
;       if (og + 1u == (tg + 1u) * b.nx) xb_add(&bar[XB_TOPGEN], 1u);
;       else XB_SPIN(xb_ld(&bar[XB_TOPGEN]) == tg, bar);
;       __builtin_amdgcn_fence(__ATOMIC_ACQUIRE, "agent");
;       xb_add(&bar[XB_XGEN(b.x)], 1u);
;     } else {
;       XB_SPIN(xb_ld(&bar[XB_XGEN(b.x)]) == gen, bar);
;       __builtin_amdgcn_fence(__ATOMIC_ACQUIRE, "agent");
.LBB0_410:
	s_and_b32 s24, s9, 0xff
	s_mov_b64 s[36:37], -1
	s_cmp_lg_u32 s24, 0
	s_mov_b64 s[40:41], -1
	s_sleep 3
	s_cbranch_scc1 .LBB0_413
	global_load_dword v2, v1, s[16:17] sc1
	s_waitcnt vmcnt(0)
	v_cmp_eq_u32_e32 vcc, 0, v2
	s_cbranch_vccnz .LBB0_415
	s_mov_b64 s[40:41], 0
	s_mov_b64 s[38:39], -1

; __device__ __forceinline__ unsigned xb_ld(unsigned* p) { return __hip_atomic_load(p, __ATOMIC_RELAXED, __HIP_MEMORY_SCOPE_AGENT); }
; __device__ __forceinline__ unsigned xb_add(unsigned* p, unsigned v) { return __hip_atomic_fetch_add(p, v, __ATOMIC_RELAXED, __HIP_MEMORY_SCOPE_AGENT); }
; #define XB_SPIN(cond, bar) do { unsigned _sp = 0; while (cond) { __builtin_amdgcn_s_sleep(1); \
;     if ((++_sp & 255u) == 0u) { if (xb_ld(&(bar)[XB_TMO])) break; if (_sp > XB_SPIN_CAP) { atomicAdd(&(bar)[XB_TMO], 1u); break; } } } } while (0)
; __device__ __forceinline__ void xcd_barrier(const XcdBarrier& b) {
;     ...
;       const unsigned tg = og / b.nx;
;       if (og + 1u == (tg + 1u) * b.nx) xb_add(&bar[XB_TOPGEN], 1u);
;       else XB_SPIN(xb_ld(&bar[XB_TOPGEN]) == tg, bar);
;       __builtin_amdgcn_fence(__ATOMIC_ACQUIRE, "agent");
;       xb_add(&bar[XB_XGEN(b.x)], 1u);
;     } else {
;       XB_SPIN(xb_ld(&bar[XB_XGEN(b.x)]) == gen, bar);
;       __builtin_amdgcn_fence(__ATOMIC_ACQUIRE, "agent");
.LBB0_427:
	s_and_b32 s24, s9, 0xff
	s_cmp_lg_u32 s24, 0
	s_mov_b64 s[38:39], -1
	s_sleep 3
	s_cbranch_scc1 .LBB0_430
	global_load_dword v1, v0, s[16:17] sc1
	s_waitcnt vmcnt(0)
	v_cmp_eq_u32_e32 vcc, 0, v1
	s_cbranch_vccnz .LBB0_432
	s_mov_b64 s[38:39], 0
	s_mov_b64 s[36:37], -1

; __device__ __forceinline__ unsigned xb_ld(unsigned* p) { return __hip_atomic_load(p, __ATOMIC_RELAXED, __HIP_MEMORY_SCOPE_AGENT); }
; __device__ __forceinline__ unsigned xb_add(unsigned* p, unsigned v) { return __hip_atomic_fetch_add(p, v, __ATOMIC_RELAXED, __HIP_MEMORY_SCOPE_AGENT); }
; #define XB_SPIN(cond, bar) do { unsigned _sp = 0; while (cond) { __builtin_amdgcn_s_sleep(1); \
;     if ((++_sp & 255u) == 0u) { if (xb_ld(&(bar)[XB_TMO])) break; if (_sp > XB_SPIN_CAP) { atomicAdd(&(bar)[XB_TMO], 1u); break; } } } } while (0)
; __device__ __forceinline__ void xcd_barrier(const XcdBarrier& b) {
;     ...
;       const unsigned tg = og / b.nx;
;       if (og + 1u == (tg + 1u) * b.nx) xb_add(&bar[XB_TOPGEN], 1u);
;       else XB_SPIN(xb_ld(&bar[XB_TOPGEN]) == tg, bar);
;       __builtin_amdgcn_fence(__ATOMIC_ACQUIRE, "agent");
;       xb_add(&bar[XB_XGEN(b.x)], 1u);
;     } else {
;       XB_SPIN(xb_ld(&bar[XB_XGEN(b.x)]) == gen, bar);
;       __builtin_amdgcn_fence(__ATOMIC_ACQUIRE, "agent");
.LBB0_500:
	s_and_b32 s36, s9, 0xff
	s_mov_b64 s[34:35], -1
	s_cmp_lg_u32 s36, 0
	s_mov_b64 s[38:39], -1
	s_sleep 3
	s_cbranch_scc1 .LBB0_503
	global_load_dword v2, v1, s[16:17] sc1
	s_waitcnt vmcnt(0)
	v_cmp_eq_u32_e32 vcc, 0, v2
	s_cbranch_vccnz .LBB0_505
	s_mov_b64 s[38:39], 0
	s_mov_b64 s[36:37], -1

; __device__ __forceinline__ unsigned xb_ld(unsigned* p) { return __hip_atomic_load(p, __ATOMIC_RELAXED, __HIP_MEMORY_SCOPE_AGENT); }
; __device__ __forceinline__ unsigned xb_add(unsigned* p, unsigned v) { return __hip_atomic_fetch_add(p, v, __ATOMIC_RELAXED, __HIP_MEMORY_SCOPE_AGENT); }
; #define XB_SPIN(cond, bar) do { unsigned _sp = 0; while (cond) { __builtin_amdgcn_s_sleep(1); \
;     if ((++_sp & 255u) == 0u) { if (xb_ld(&(bar)[XB_TMO])) break; if (_sp > XB_SPIN_CAP) { atomicAdd(&(bar)[XB_TMO], 1u); break; } } } } while (0)
; __device__ __forceinline__ void xcd_barrier(const XcdBarrier& b) {
;     ...
;       const unsigned tg = og / b.nx;
;       if (og + 1u == (tg + 1u) * b.nx) xb_add(&bar[XB_TOPGEN], 1u);
;       else XB_SPIN(xb_ld(&bar[XB_TOPGEN]) == tg, bar);
;       __builtin_amdgcn_fence(__ATOMIC_ACQUIRE, "agent");
;       xb_add(&bar[XB_XGEN(b.x)], 1u);
;     } else {
;       XB_SPIN(xb_ld(&bar[XB_XGEN(b.x)]) == gen, bar);
;       __builtin_amdgcn_fence(__ATOMIC_ACQUIRE, "agent");
.LBB0_517:
	s_and_b32 s34, s9, 0xff
	s_cmp_lg_u32 s34, 0
	s_mov_b64 s[36:37], -1
	s_sleep 3
	s_cbranch_scc1 .LBB0_520
	global_load_dword v1, v0, s[16:17] sc1
	s_waitcnt vmcnt(0)
	v_cmp_eq_u32_e32 vcc, 0, v1
	s_cbranch_vccnz .LBB0_522
	s_mov_b64 s[36:37], 0
	s_mov_b64 s[34:35], -1

; __device__ __forceinline__ unsigned xb_ld(unsigned* p) { return __hip_atomic_load(p, __ATOMIC_RELAXED, __HIP_MEMORY_SCOPE_AGENT); }
; __device__ __forceinline__ unsigned xb_add(unsigned* p, unsigned v) { return __hip_atomic_fetch_add(p, v, __ATOMIC_RELAXED, __HIP_MEMORY_SCOPE_AGENT); }
; #define XB_SPIN(cond, bar) do { unsigned _sp = 0; while (cond) { __builtin_amdgcn_s_sleep(1); \
;     if ((++_sp & 255u) == 0u) { if (xb_ld(&(bar)[XB_TMO])) break; if (_sp > XB_SPIN_CAP) { atomicAdd(&(bar)[XB_TMO], 1u); break; } } } } while (0)
; __device__ __forceinline__ void xcd_barrier(const XcdBarrier& b) {
;     ...
;       const unsigned tg = og / b.nx;
;       if (og + 1u == (tg + 1u) * b.nx) xb_add(&bar[XB_TOPGEN], 1u);
;       else XB_SPIN(xb_ld(&bar[XB_TOPGEN]) == tg, bar);
;       __builtin_amdgcn_fence(__ATOMIC_ACQUIRE, "agent");
;       xb_add(&bar[XB_XGEN(b.x)], 1u);
;     } else {
;       XB_SPIN(xb_ld(&bar[XB_XGEN(b.x)]) == gen, bar);
;       __builtin_amdgcn_fence(__ATOMIC_ACQUIRE, "agent");
.LBB0_560:
	s_and_b32 s9, s8, 0xff
	s_mov_b64 s[28:29], -1
	s_cmp_lg_u32 s9, 0
	s_mov_b64 s[34:35], -1
	s_sleep 3
	s_cbranch_scc1 .LBB0_563
	global_load_dword v2, v1, s[14:15] sc1
	s_waitcnt vmcnt(0)
	v_cmp_eq_u32_e32 vcc, 0, v2
	s_cbranch_vccnz .LBB0_565
	s_mov_b64 s[34:35], 0
	s_mov_b64 s[30:31], -1

; __device__ __forceinline__ unsigned xb_ld(unsigned* p) { return __hip_atomic_load(p, __ATOMIC_RELAXED, __HIP_MEMORY_SCOPE_AGENT); }
; __device__ __forceinline__ unsigned xb_add(unsigned* p, unsigned v) { return __hip_atomic_fetch_add(p, v, __ATOMIC_RELAXED, __HIP_MEMORY_SCOPE_AGENT); }
; #define XB_SPIN(cond, bar) do { unsigned _sp = 0; while (cond) { __builtin_amdgcn_s_sleep(1); \
;     if ((++_sp & 255u) == 0u) { if (xb_ld(&(bar)[XB_TMO])) break; if (_sp > XB_SPIN_CAP) { atomicAdd(&(bar)[XB_TMO], 1u); break; } } } } while (0)
; __device__ __forceinline__ void xcd_barrier(const XcdBarrier& b) {
;     ...
;       const unsigned tg = og / b.nx;
;       if (og + 1u == (tg + 1u) * b.nx) xb_add(&bar[XB_TOPGEN], 1u);
;       else XB_SPIN(xb_ld(&bar[XB_TOPGEN]) == tg, bar);
;       __builtin_amdgcn_fence(__ATOMIC_ACQUIRE, "agent");
;       xb_add(&bar[XB_XGEN(b.x)], 1u);
;     } else {
;       XB_SPIN(xb_ld(&bar[XB_XGEN(b.x)]) == gen, bar);
;       __builtin_amdgcn_fence(__ATOMIC_ACQUIRE, "agent");
.LBB0_577:
	s_and_b32 s9, s8, 0xff
	s_cmp_lg_u32 s9, 0
	s_mov_b64 s[30:31], -1
	s_sleep 3
	s_cbranch_scc1 .LBB0_580
	global_load_dword v1, v0, s[14:15] sc1
	s_waitcnt vmcnt(0)
	v_cmp_eq_u32_e32 vcc, 0, v1
	s_cbranch_vccnz .LBB0_582
	s_mov_b64 s[30:31], 0
	s_mov_b64 s[28:29], -1

; __device__ __forceinline__ unsigned xb_ld(unsigned* p) { return __hip_atomic_load(p, __ATOMIC_RELAXED, __HIP_MEMORY_SCOPE_AGENT); }
; __device__ __forceinline__ unsigned xb_add(unsigned* p, unsigned v) { return __hip_atomic_fetch_add(p, v, __ATOMIC_RELAXED, __HIP_MEMORY_SCOPE_AGENT); }
; #define XB_SPIN(cond, bar) do { unsigned _sp = 0; while (cond) { __builtin_amdgcn_s_sleep(1); \
;     if ((++_sp & 255u) == 0u) { if (xb_ld(&(bar)[XB_TMO])) break; if (_sp > XB_SPIN_CAP) { atomicAdd(&(bar)[XB_TMO], 1u); break; } } } } while (0)
; __device__ __forceinline__ void xcd_barrier(const XcdBarrier& b) {
;     ...
;       const unsigned tg = og / b.nx;
;       if (og + 1u == (tg + 1u) * b.nx) xb_add(&bar[XB_TOPGEN], 1u);
;       else XB_SPIN(xb_ld(&bar[XB_TOPGEN]) == tg, bar);
;       __builtin_amdgcn_fence(__ATOMIC_ACQUIRE, "agent");
;       xb_add(&bar[XB_XGEN(b.x)], 1u);
;     } else {
;       XB_SPIN(xb_ld(&bar[XB_XGEN(b.x)]) == gen, bar);
;       __builtin_amdgcn_fence(__ATOMIC_ACQUIRE, "agent");
.LBB0_746:
	s_and_b32 s24, s28, 0xff
	s_mov_b64 s[16:17], -1
	s_cmp_lg_u32 s24, 0
	s_mov_b64 s[26:27], -1
	s_sleep 3
	s_cbranch_scc1 .LBB0_749
	global_load_dword v2, v1, s[8:9] sc1
	s_waitcnt vmcnt(0)
	v_cmp_eq_u32_e32 vcc, 0, v2
	s_cbranch_vccnz .LBB0_751
	s_mov_b64 s[26:27], 0
	s_mov_b64 s[24:25], -1

; __device__ __forceinline__ unsigned xb_ld(unsigned* p) { return __hip_atomic_load(p, __ATOMIC_RELAXED, __HIP_MEMORY_SCOPE_AGENT); }
; __device__ __forceinline__ unsigned xb_add(unsigned* p, unsigned v) { return __hip_atomic_fetch_add(p, v, __ATOMIC_RELAXED, __HIP_MEMORY_SCOPE_AGENT); }
; #define XB_SPIN(cond, bar) do { unsigned _sp = 0; while (cond) { __builtin_amdgcn_s_sleep(1); \
;     if ((++_sp & 255u) == 0u) { if (xb_ld(&(bar)[XB_TMO])) break; if (_sp > XB_SPIN_CAP) { atomicAdd(&(bar)[XB_TMO], 1u); break; } } } } while (0)
; __device__ __forceinline__ void xcd_barrier(const XcdBarrier& b) {
;     ...
;       const unsigned tg = og / b.nx;
;       if (og + 1u == (tg + 1u) * b.nx) xb_add(&bar[XB_TOPGEN], 1u);
;       else XB_SPIN(xb_ld(&bar[XB_TOPGEN]) == tg, bar);
;       __builtin_amdgcn_fence(__ATOMIC_ACQUIRE, "agent");
;       xb_add(&bar[XB_XGEN(b.x)], 1u);
;     } else {
;       XB_SPIN(xb_ld(&bar[XB_XGEN(b.x)]) == gen, bar);
;       __builtin_amdgcn_fence(__ATOMIC_ACQUIRE, "agent");
.LBB0_763:
	s_and_b32 s16, s26, 0xff
	s_cmp_lg_u32 s16, 0
	s_mov_b64 s[22:23], -1
	s_sleep 3
	s_cbranch_scc1 .LBB0_766
	global_load_dword v1, v0, s[8:9] sc1
	s_waitcnt vmcnt(0)
	v_cmp_eq_u32_e32 vcc, 0, v1
	s_cbranch_vccnz .LBB0_768
	s_mov_b64 s[22:23], 0
	s_mov_b64 s[16:17], -1
